# attention: software-pipelined QK/softmax/PV interleave, in-place exp, m=0 fast path without per-element max subtraction (general path kept)
# speedup vs baseline: 1.0219x; 1.0035x over previous
; #define ATT_LOADK(rk, rr, kt_) do { if (MODE == 3 && (kt_) > 1) break; rk = *(const u32x4*)(gkn + (size_t)(kt_) * 64 * 512); rr = *(const u32x4*)(gkr + (size_t)(kt_) * 64 * 32); } while (0)
; #define ATT_LOADV(rv, kt_) do { if (MODE == 3 && (kt_) > 1) break; rv = *(const u32x4*)(gvt + (size_t)(kt_) * 64); } while (0)
; #define ATT_WRITEK(rk, rr, buf) do { LAS unsigned char* nb_ = lds + (buf) * KBUF; *(LAS u32x4*)(nb_ + skn) = rk; if (tid < 256) *(LAS u32x4*)(nb_ + skr) = rr; } while (0)
; #define ATT_WRITEV(rv, buf) do { LAS u32x2* p_ = (LAS u32x2*)(ldsv + (buf) * VBUF + svt); u32x2 lo_ = {rv[0], rv[1]}, hi_ = {rv[2], rv[3]}; p_[0] = lo_; p_[1] = hi_; } while (0)
; template <int MODE>
; __device__ __forceinline__ void attn_phase(const Args& a, bool do_ctx, LAS unsigned char* lds, const int wid_s) {
;     ...
;         __syncthreads();
;         f32x16 ot[2], sa[2], sb[2];
; #pragma unroll
;         for (int i = 0; i < 16; ++i) { ot[0][i] = 0.f; ot[1][i] = 0.f; }
;         float mrun = -3.0e38f, lsum = 0.f;
;         attn_qk<MODE>(lds, qf, sa, ql, hf);
;         __syncthreads();
;         for (int t = 0; t < nkt; t += 2) {
;             if (t + 2 < nkt) ATT_LOADK(kK, kR, t + 2);
;             ATT_LOADV(vV, t + 1);
;             attn_qk<MODE>(lds + KBUF, qf, sb, ql, hf);
;             __builtin_amdgcn_sched_barrier(0);
;             attn_pv<MODE>(ldsv, sa, ot, mrun, lsum, ql, hf, lane);
;             if (t + 2 < nkt) ATT_WRITEK(kK, kR, 0);
;             ATT_WRITEV(vV, 1);
;             __syncthreads();
;             if (t + 3 < nkt) ATT_LOADK(kK, kR, t + 3);
;             if (t + 2 < nkt) ATT_LOADV(vV, t + 2);
;             if (t + 2 < nkt) attn_qk<MODE>(lds, qf, sa, ql, hf);
;             __builtin_amdgcn_sched_barrier(0);
;             attn_pv<MODE>(ldsv + VBUF, sb, ot, mrun, lsum, ql, hf, lane);
;             if (t + 3 < nkt) ATT_WRITEK(kK, kR, 1);
;             if (t + 2 < nkt) ATT_WRITEV(vV, 0);
;             __syncthreads();
;         }
.LBB0_433:
	s_or_b64 exec, exec, s[2:3]
	s_movk_i32 s2, 0x4200
	v_mad_i64_i32 v[84:85], s[2:3], v8, s2, 0
	s_waitcnt lgkmcnt(0)
	s_barrier
	ds_read_b128 v[0:3], v165 offset:6656
	ds_read_b128 v[4:7], v165
	ds_read_b128 v[8:11], v165 offset:32
	ds_read_b128 v[20:23], v165 offset:6688
	ds_read_b128 v[24:27], v165 offset:64
	ds_read_b128 v[28:31], v165 offset:6720
	ds_read_b128 v[64:67], v165 offset:96
	ds_read_b128 v[68:71], v165 offset:6752
	v_ashrrev_i32_e32 v145, 31, v144
	s_waitcnt lgkmcnt(6)
	v_mfma_f32_32x32x16_bf16 v[48:63], v[4:7], v[112:115], 0
	s_mov_b32 s8, s77
	s_mov_b32 s9, s77
	s_mov_b32 s10, s77
	s_mov_b32 s11, s77
	s_mov_b32 s12, s77
	s_mov_b32 s13, s77
	s_mov_b32 s14, s77
	v_mfma_f32_32x32x16_bf16 v[32:47], v[0:3], v[112:115], 0
	s_mov_b32 s15, s77
	s_mov_b32 s16, s77
	s_mov_b32 s17, s77
	s_mov_b32 s18, s77
	s_mov_b32 s19, s77
	s_mov_b32 s20, s77
	s_mov_b32 s21, s77
	s_waitcnt lgkmcnt(5)
	v_mfma_f32_32x32x16_bf16 v[48:63], v[8:11], v[96:99], v[48:63]
	s_mov_b32 s22, s77
	s_mov_b32 s23, s77
	v_mov_b64_e32 v[0:1], s[8:9]
	v_mov_b64_e32 v[2:3], s[10:11]
	v_mov_b64_e32 v[4:5], s[12:13]
	v_mov_b64_e32 v[6:7], s[14:15]
	v_mov_b64_e32 v[8:9], s[16:17]
	s_waitcnt lgkmcnt(4)
	v_mfma_f32_32x32x16_bf16 v[32:47], v[20:23], v[96:99], v[32:47]
	v_mov_b64_e32 v[10:11], s[18:19]
	v_mov_b64_e32 v[12:13], s[20:21]
	v_mov_b64_e32 v[14:15], s[22:23]
	ds_read_b128 v[20:23], v165 offset:128
	ds_read_b128 v[72:75], v165 offset:160
	ds_read_b128 v[76:79], v165 offset:6784
	ds_read_b128 v[80:83], v165 offset:6816
	s_waitcnt lgkmcnt(7)
	v_mfma_f32_32x32x16_bf16 v[48:63], v[24:27], v[100:103], v[48:63]
	v_lshl_add_u64 v[16:17], v[136:137], 0, v[16:17]
	v_lshl_add_u64 v[146:147], v[16:17], 0, s[76:77]
	v_lshl_add_u64 v[148:149], v[132:133], 0, v[18:19]
	v_lshl_add_u64 v[150:151], v[136:137], 0, v[84:85]
	v_mov_b32_e32 v143, 0xff61b1e6
	s_mov_b32 s90, 0
	v_mov_b32_e32 v167, 0
	s_mov_b32 s12, 3
	v_readlane_b32 s18, v247, 57
	v_readlane_b32 s19, v247, 58
	s_nop 3
	s_add_u32 s80, s18, 0x31a07000
	s_addc_u32 s81, s19, 0
	s_add_u32 s82, s18, 0x33ae9000
	s_addc_u32 s83, s19, 0
	s_add_u32 s84, s18, 0x33cf7000
	s_addc_u32 s85, s19, 0
	s_waitcnt lgkmcnt(6)
	v_mfma_f32_32x32x16_bf16 v[32:47], v[28:31], v[100:103], v[32:47]
	s_waitcnt lgkmcnt(0)
	s_barrier
	v_mfma_f32_32x32x16_bf16 v[48:63], v[64:67], v[104:107], v[48:63]
	v_mfma_f32_32x32x16_bf16 v[32:47], v[68:71], v[104:107], v[32:47]
	v_mfma_f32_32x32x16_bf16 v[48:63], v[20:23], v[108:111], v[48:63]
	v_mov_b64_e32 v[30:31], v[14:15]
	v_mov_b64_e32 v[28:29], v[12:13]
	v_mov_b64_e32 v[26:27], v[10:11]
	v_mov_b64_e32 v[24:25], v[8:9]
	v_mov_b64_e32 v[22:23], v[6:7]
	v_mov_b64_e32 v[20:21], v[4:5]
	v_mov_b64_e32 v[18:19], v[2:3]
	v_mfma_f32_32x32x16_bf16 v[32:47], v[76:79], v[108:111], v[32:47]
	v_mov_b64_e32 v[16:17], v[0:1]
	v_mfma_f32_32x32x16_bf16 v[48:63], v[72:75], v[116:119], v[48:63]
	v_mfma_f32_32x32x16_bf16 v[32:47], v[80:83], v[116:119], v[32:47]
	s_branch .LBB0_435
.LBB0_434:
	s_add_u32 s80, s80, 0x20000
	s_addc_u32 s81, s81, 0
	s_add_u32 s82, s82, 0x2000
	s_addc_u32 s83, s83, 0
	s_add_u32 s84, s84, 0x100
	s_addc_u32 s85, s85, 0
	s_add_i32 s12, s12, 2
	s_cmp_ge_u32 s13, s25
	s_waitcnt lgkmcnt(0)
	s_barrier
	s_cbranch_scc1 .LBB0_421

; template <int MODE>
; __device__ __forceinline__ void attn_qk(const LAS unsigned char* kb_, const bf16x8 (&qf)[6], f32x16 (&st)[2], const int ql, const int hf) {
;     ...
;     bf16x8 ka[4], kc[4], ke[4];
; #pragma unroll
;     for (int s = 0; s < 2; ++s) { ka[2 * s] = ATT_KF(0, s); ka[2 * s + 1] = ATT_KF(1, s); }
; #pragma unroll
;     for (int s = 2; s < 4; ++s) { kc[2 * (s - 2)] = ATT_KF(0, s); kc[2 * (s - 2) + 1] = ATT_KF(1, s); }
;     __builtin_amdgcn_sched_barrier(0);
; #pragma unroll
;     for (int i = 0; i < 16; ++i) { st[0][i] = 0.f; st[1][i] = 0.f; }
; #pragma unroll
;     for (int s = 0; s < 2; ++s) { st[0] = ATT_MMA(ka[2 * s], qf[s], st[0], 0, 0, 0); st[1] = ATT_MMA(ka[2 * s + 1], qf[s], st[1], 0, 0, 0); }
;     __builtin_amdgcn_sched_barrier(0);
; #pragma unroll
;     for (int s = 4; s < 6; ++s) { ke[2 * (s - 4)] = ATT_KF(0, s); ke[2 * (s - 4) + 1] = ATT_KF(1, s); }
;     __builtin_amdgcn_sched_barrier(0);
; #pragma unroll
;     for (int s = 2; s < 4; ++s) { st[0] = ATT_MMA(kc[2 * (s - 2)], qf[s], st[0], 0, 0, 0); st[1] = ATT_MMA(kc[2 * (s - 2) + 1], qf[s], st[1], 0, 0, 0); }
; #pragma unroll
;     for (int s = 4; s < 6; ++s) { st[0] = ATT_MMA(ke[2 * (s - 4)], qf[s], st[0], 0, 0, 0); st[1] = ATT_MMA(ke[2 * (s - 4) + 1], qf[s], st[1], 0, 0, 0); }
;     ...
; }
; template <int MODE>
; __device__ __forceinline__ void attn_pv(const LAS unsigned char* vb_, f32x16 (&st)[2], f32x16 (&ot)[2], float& mrun, float& lsum, const int ql, const int hf, const int lane) {
;     if (MODE != 1) {
;     float mx = max3f(st[0][0], st[1][0], st[0][1]), my = max3f(st[1][1], st[0][2], st[1][2]);
; #pragma unroll
;     for (int i = 3; i < 15; i += 2) { mx = max3f(mx, st[0][i], st[1][i]); my = max3f(my, st[0][i + 1], st[1][i + 1]); }
;     mx = max3f(mx, st[0][15], st[1][15]); mx = max3f(mx, my, my);
;     if (__builtin_amdgcn_ballot_w64(mx > mrun + 8.0f) != 0ull) {
;         mx = fmaxf(mx, shx32(mx, lane));
;         const float mnew = (mx > mrun + 8.0f) ? mx : mrun;
;         const float alpha = fexp2(mrun - mnew);
;         mrun = mnew; lsum *= alpha;
; #pragma unroll
;         for (int i = 0; i < 16; ++i) { ot[0][i] *= alpha; ot[1][i] *= alpha; }
;     }
;     float ps = 0.f;
; #pragma unroll
;     for (int kb = 0; kb < 2; ++kb)
; #pragma unroll
;         for (int i = 0; i < 16; ++i) { const float p = fexp2(st[kb][i] - mrun); st[kb][i] = p; ps += p; }
;     lsum += ps;
.LBB0_437:
	global_load_dwordx4 v[128:131], v150, s[84:85] offset:128
	ds_read_b128 v[64:67], v165 offset:13312
	ds_read_b128 v[168:171], v165 offset:13344
	ds_read_b128 v[68:71], v165 offset:19968
	ds_read_b128 v[172:175], v165 offset:20000
	ds_read_b128 v[176:179], v165 offset:13376
	ds_read_b128 v[180:183], v165 offset:13408
	ds_read_b128 v[184:187], v165 offset:20032
	ds_read_b128 v[188:191], v165 offset:20064
	ds_read2_b64 v[206:209], v241 offset0:32 offset1:34
	ds_read2_b64 v[210:213], v240 offset1:2
	ds_read2_b64 v[214:217], v241 offset0:36 offset1:38
	ds_read2_b64 v[218:221], v240 offset0:4 offset1:6
	ds_read2_b64 v[222:225], v241 offset0:40 offset1:42
	ds_read2_b64 v[226:229], v240 offset0:8 offset1:10
	ds_read2_b64 v[236:239], v240 offset0:12 offset1:14
	v_max3_f32 v156, v48, v32, v49
	v_max3_f32 v157, v33, v50, v34
	v_max3_f32 v156, v156, v51, v35
	v_max3_f32 v157, v157, v52, v36
	v_max3_f32 v156, v156, v53, v37
	v_max3_f32 v157, v157, v54, v38
	v_max3_f32 v156, v156, v55, v39
	v_max3_f32 v157, v157, v56, v40
	v_max3_f32 v156, v156, v57, v41
	v_max3_f32 v157, v157, v58, v42
	v_max3_f32 v156, v156, v59, v43
	v_max3_f32 v157, v157, v60, v44
	v_max3_f32 v156, v156, v61, v45
	v_max3_f32 v157, v157, v62, v46
	v_max3_f32 v156, v156, v63, v47
	v_max3_f32 v157, v156, v157, v157
	v_add_f32_e32 v156, 0x41000000, v143
	v_cmp_gt_f32_e32 vcc, v157, v156
	s_cbranch_vccz .Latt_e_nors
	ds_bpermute_b32 v231, v163, v157
	v_max_f32_e32 v157, v157, v157
	s_waitcnt lgkmcnt(0)
	v_max_f32_e32 v231, v231, v231
	v_max_f32_e32 v157, v157, v231
	v_cmp_gt_f32_e32 vcc, v157, v156
	s_nop 1
	v_cndmask_b32_e32 v157, v143, v157, vcc
	v_add_f32_e32 v231, 0x41400000, v157
	s_mov_b32 s2, 0x41a00000
	v_cmp_le_f32_e64 vcc, |v231|, s2
	s_nop 1
	v_cndmask_b32_e32 v157, v157, v201, vcc
	v_sub_f32_e32 v143, v143, v157
	v_exp_f32_e32 v156, v143
	v_mov_b32_e32 v143, v157
	v_mul_f32_e32 v167, v167, v156
	v_pk_mul_f32 v[14:15], v[14:15], v[156:157] op_sel_hi:[1,0]
	v_pk_mul_f32 v[12:13], v[12:13], v[156:157] op_sel_hi:[1,0]
	v_pk_mul_f32 v[10:11], v[10:11], v[156:157] op_sel_hi:[1,0]
	v_pk_mul_f32 v[8:9], v[8:9], v[156:157] op_sel_hi:[1,0]
	v_pk_mul_f32 v[6:7], v[6:7], v[156:157] op_sel_hi:[1,0]
	v_pk_mul_f32 v[4:5], v[4:5], v[156:157] op_sel_hi:[1,0]
	v_pk_mul_f32 v[2:3], v[2:3], v[156:157] op_sel_hi:[1,0]
	v_pk_mul_f32 v[0:1], v[0:1], v[156:157] op_sel_hi:[1,0]
	v_pk_mul_f32 v[30:31], v[30:31], v[156:157] op_sel_hi:[1,0]
	v_pk_mul_f32 v[28:29], v[28:29], v[156:157] op_sel_hi:[1,0]
	v_pk_mul_f32 v[26:27], v[26:27], v[156:157] op_sel_hi:[1,0]
	v_pk_mul_f32 v[24:25], v[24:25], v[156:157] op_sel_hi:[1,0]
	v_pk_mul_f32 v[22:23], v[22:23], v[156:157] op_sel_hi:[1,0]
	v_pk_mul_f32 v[20:21], v[20:21], v[156:157] op_sel_hi:[1,0]
	v_pk_mul_f32 v[18:19], v[18:19], v[156:157] op_sel_hi:[1,0]
	v_pk_mul_f32 v[16:17], v[16:17], v[156:157] op_sel_hi:[1,0]
	v_cmp_neq_f32_e32 vcc, 0, v143
	s_nop 1
	s_cmp_eq_u64 vcc, 0
	s_cselect_b32 s90, 1, 0
.Latt_e_nors:
	s_cmp_lg_u32 s90, 0
	s_cbranch_scc1 .Latt_e_nors_fast
	s_waitcnt lgkmcnt(14)
	v_mfma_f32_32x32x16_bf16 v[80:95], v[64:67], v[112:115], 0
	v_sub_f32_e32 v48, v48, v143
	v_sub_f32_e32 v49, v49, v143
	v_sub_f32_e32 v50, v50, v143
	v_sub_f32_e32 v51, v51, v143
	v_sub_f32_e32 v52, v52, v143
	v_sub_f32_e32 v53, v53, v143
	v_sub_f32_e32 v54, v54, v143
	v_sub_f32_e32 v55, v55, v143
	s_waitcnt lgkmcnt(12)
	v_mfma_f32_32x32x16_bf16 v[64:79], v[68:71], v[112:115], 0
	v_exp_f32_e32 v48, v48
	v_exp_f32_e32 v49, v49
	v_exp_f32_e32 v50, v50
	v_exp_f32_e32 v51, v51
	v_mfma_f32_32x32x16_bf16 v[80:95], v[168:171], v[96:99], v[80:95]
	v_exp_f32_e32 v52, v52
	v_exp_f32_e32 v53, v53
	v_exp_f32_e32 v54, v54
	v_exp_f32_e32 v55, v55
	s_waitcnt lgkmcnt(11)
	v_mfma_f32_32x32x16_bf16 v[64:79], v[172:175], v[96:99], v[64:79]
	ds_read_b128 v[168:171], v165 offset:13440
	ds_read_b128 v[172:175], v165 offset:13472
	ds_read_b128 v[192:195], v165 offset:20096
	ds_read_b128 v[196:199], v165 offset:20128
	v_cvt_pk_bf16_f32 v152, v48, v49
	v_cvt_pk_bf16_f32 v153, v50, v51
	v_cvt_pk_bf16_f32 v154, v52, v53
	v_cvt_pk_bf16_f32 v155, v54, v55
	v_add_f32_e32 v230, 0, v48
	v_add_f32_e32 v230, v49, v230
	v_add_f32_e32 v230, v50, v230
	v_add_f32_e32 v230, v51, v230
	v_add_f32_e32 v230, v52, v230
	v_add_f32_e32 v230, v53, v230
	v_add_f32_e32 v230, v54, v230
	v_add_f32_e32 v230, v55, v230
	s_waitcnt lgkmcnt(14)
	v_mfma_f32_32x32x16_bf16 v[80:95], v[176:179], v[100:103], v[80:95]
	ds_read2_b64 a[0:3], v241 offset0:44 offset1:46
	v_sub_f32_e32 v56, v56, v143
	v_sub_f32_e32 v57, v57, v143
	v_sub_f32_e32 v58, v58, v143
	v_sub_f32_e32 v59, v59, v143
	v_sub_f32_e32 v60, v60, v143
	v_sub_f32_e32 v61, v61, v143
	v_sub_f32_e32 v62, v62, v143
	v_sub_f32_e32 v63, v63, v143
	s_waitcnt lgkmcnt(13)
	v_mfma_f32_32x32x16_bf16 v[64:79], v[184:187], v[100:103], v[64:79]
	v_exp_f32_e32 v56, v56
	v_exp_f32_e32 v57, v57
	v_exp_f32_e32 v58, v58
	v_exp_f32_e32 v59, v59
	v_mfma_f32_32x32x16_bf16 v[80:95], v[180:183], v[104:107], v[80:95]
	v_exp_f32_e32 v60, v60
	v_exp_f32_e32 v61, v61
	v_exp_f32_e32 v62, v62
	v_exp_f32_e32 v63, v63
	s_waitcnt lgkmcnt(12)
	v_mfma_f32_32x32x16_bf16 v[64:79], v[188:191], v[104:107], v[64:79]
	s_waitcnt lgkmcnt(10)
	v_mfma_f32_32x32x16_bf16 v[16:31], v[206:209], v[152:155], v[16:31]
	v_cvt_pk_bf16_f32 v48, v56, v57
	v_cvt_pk_bf16_f32 v49, v58, v59
	v_cvt_pk_bf16_f32 v50, v60, v61
	v_cvt_pk_bf16_f32 v51, v62, v63
	v_mfma_f32_32x32x16_bf16 v[0:15], v[210:213], v[152:155], v[0:15]
	v_add_f32_e32 v230, v56, v230
	v_add_f32_e32 v230, v57, v230
	v_add_f32_e32 v230, v58, v230
	v_add_f32_e32 v230, v59, v230
	v_add_f32_e32 v230, v60, v230
	v_add_f32_e32 v230, v61, v230
	v_add_f32_e32 v230, v62, v230
	v_add_f32_e32 v230, v63, v230
	s_waitcnt lgkmcnt(4)
; #define LAS __attribute__((address_space(3)))
; #define ATT_MMA(a_, b_, c_, x_, y_, z_) att_mma<MODE>(a_, b_, c_)
; template <int MODE>
; __device__ __forceinline__ void attn_qk(const LAS unsigned char* kb_, const bf16x8 (&qf)[6], f32x16 (&st)[2], const int ql, const int hf) {
;     ...
;     bf16x8 ka[4], kc[4], ke[4];
; #pragma unroll
;     for (int s = 0; s < 2; ++s) { ka[2 * s] = ATT_KF(0, s); ka[2 * s + 1] = ATT_KF(1, s); }
; #pragma unroll
;     for (int s = 2; s < 4; ++s) { kc[2 * (s - 2)] = ATT_KF(0, s); kc[2 * (s - 2) + 1] = ATT_KF(1, s); }
;     __builtin_amdgcn_sched_barrier(0);
; #pragma unroll
;     for (int i = 0; i < 16; ++i) { st[0][i] = 0.f; st[1][i] = 0.f; }
; #pragma unroll
;     for (int s = 0; s < 2; ++s) { st[0] = ATT_MMA(ka[2 * s], qf[s], st[0], 0, 0, 0); st[1] = ATT_MMA(ka[2 * s + 1], qf[s], st[1], 0, 0, 0); }
;     __builtin_amdgcn_sched_barrier(0);
; #pragma unroll
;     for (int s = 4; s < 6; ++s) { ke[2 * (s - 4)] = ATT_KF(0, s); ke[2 * (s - 4) + 1] = ATT_KF(1, s); }
;     __builtin_amdgcn_sched_barrier(0);
; #pragma unroll
; template <int MODE>
; __device__ __forceinline__ void attn_pv(const LAS unsigned char* vb_, f32x16 (&st)[2], f32x16 (&ot)[2], float& mrun, float& lsum, const int ql, const int hf, const int lane) {
;     ...
;     float ps = 0.f;
; #pragma unroll
;     for (int kb = 0; kb < 2; ++kb)
; #pragma unroll
;         for (int i = 0; i < 16; ++i) { const float p = fexp2(st[kb][i] - mrun); st[kb][i] = p; ps += p; }
;     lsum += ps;
;     } else lsum += st[0][0];
; #pragma unroll
;     for (int kb = 0; kb < 2; ++kb)
; #pragma unroll
;         for (int sI = 0; sI < 2; ++sI) {
;             u32x4 pw = {pk_bf16(st[kb][8 * sI + 0], st[kb][8 * sI + 1]), pk_bf16(st[kb][8 * sI + 2], st[kb][8 * sI + 3]),
;                         pk_bf16(st[kb][8 * sI + 4], st[kb][8 * sI + 5]), pk_bf16(st[kb][8 * sI + 6], st[kb][8 * sI + 7])};
;             const bf16x8 pf = __builtin_bit_cast(bf16x8, pw);
; #pragma unroll
;             for (int db = 0; db < 2; ++db) {
;                 const LAS unsigned char* vp = vb_ + (db * 32 + ql) * VROW + (kb * 32 + 16 * sI + 4 * hf) * 2;
;                 const u32x2 v0 = *(const LAS u32x2*)vp, v1 = *(const LAS u32x2*)(vp + 16);
;                 u32x4 vw = {v0[0], v0[1], v1[0], v1[1]};
;                 ot[db] = att_mma<MODE>(__builtin_bit_cast(bf16x8, vw), pf, ot[db]);
;             }
;         }
; }
	v_mfma_f32_32x32x16_bf16 v[80:95], v[168:171], v[108:111], v[80:95]
	v_sub_f32_e32 v32, v32, v143
	v_sub_f32_e32 v33, v33, v143
	v_sub_f32_e32 v34, v34, v143
	v_sub_f32_e32 v35, v35, v143
	v_sub_f32_e32 v36, v36, v143
	v_sub_f32_e32 v37, v37, v143
	v_sub_f32_e32 v38, v38, v143
	v_sub_f32_e32 v39, v39, v143
	v_mfma_f32_32x32x16_bf16 v[16:31], v[214:217], v[48:51], v[16:31]
	v_exp_f32_e32 v32, v32
	v_exp_f32_e32 v33, v33
	v_exp_f32_e32 v34, v34
	v_exp_f32_e32 v35, v35
	v_mfma_f32_32x32x16_bf16 v[0:15], v[218:221], v[48:51], v[0:15]
	v_exp_f32_e32 v36, v36
	v_exp_f32_e32 v37, v37
	v_exp_f32_e32 v38, v38
	v_exp_f32_e32 v39, v39
	s_waitcnt lgkmcnt(2)
	v_mfma_f32_32x32x16_bf16 v[64:79], v[192:195], v[108:111], v[64:79]
	v_cvt_pk_bf16_f32 v152, v32, v33
	v_cvt_pk_bf16_f32 v153, v34, v35
	v_cvt_pk_bf16_f32 v154, v36, v37
	v_cvt_pk_bf16_f32 v155, v38, v39
	v_mfma_f32_32x32x16_bf16 v[80:95], v[172:175], v[116:119], v[80:95]
	v_add_f32_e32 v230, v32, v230
	v_add_f32_e32 v230, v33, v230
	v_add_f32_e32 v230, v34, v230
	v_add_f32_e32 v230, v35, v230
	v_add_f32_e32 v230, v36, v230
	v_add_f32_e32 v230, v37, v230
	v_add_f32_e32 v230, v38, v230
	v_add_f32_e32 v230, v39, v230
	s_waitcnt lgkmcnt(1)
	v_mfma_f32_32x32x16_bf16 v[64:79], v[196:199], v[116:119], v[64:79]
	v_sub_f32_e32 v40, v40, v143
	v_sub_f32_e32 v41, v41, v143
	v_sub_f32_e32 v42, v42, v143
	v_sub_f32_e32 v43, v43, v143
	v_sub_f32_e32 v44, v44, v143
	v_sub_f32_e32 v45, v45, v143
	v_sub_f32_e32 v46, v46, v143
	v_sub_f32_e32 v47, v47, v143
	v_mfma_f32_32x32x16_bf16 v[16:31], v[222:225], v[152:155], v[16:31]
	v_exp_f32_e32 v40, v40
	v_exp_f32_e32 v41, v41
	v_exp_f32_e32 v42, v42
	v_exp_f32_e32 v43, v43
	v_mfma_f32_32x32x16_bf16 v[0:15], v[226:229], v[152:155], v[0:15]
	v_exp_f32_e32 v44, v44
	v_exp_f32_e32 v45, v45
	v_exp_f32_e32 v46, v46
	v_exp_f32_e32 v47, v47
	v_cvt_pk_bf16_f32 v48, v40, v41
	v_cvt_pk_bf16_f32 v49, v42, v43
	v_cvt_pk_bf16_f32 v50, v44, v45
	v_cvt_pk_bf16_f32 v51, v46, v47
	v_add_f32_e32 v230, v40, v230
	v_add_f32_e32 v230, v41, v230
	v_add_f32_e32 v230, v42, v230
	v_add_f32_e32 v230, v43, v230
	v_add_f32_e32 v230, v44, v230
	v_add_f32_e32 v230, v45, v230
	v_add_f32_e32 v230, v46, v230
	v_add_f32_e32 v230, v47, v230
	v_add_f32_e32 v167, v167, v230
	s_waitcnt lgkmcnt(0)
	v_mfma_f32_32x32x16_bf16 v[0:15], v[236:239], v[48:51], v[0:15]
	v_mfma_f32_32x32x16_bf16 v[16:31], a[0:3], v[48:51], v[16:31]
	s_branch .Latt_e_nors_join
.Latt_e_nors_fast:
	s_waitcnt lgkmcnt(14)
	v_mfma_f32_32x32x16_bf16 v[80:95], v[64:67], v[112:115], 0
	s_waitcnt lgkmcnt(12)
	v_mfma_f32_32x32x16_bf16 v[64:79], v[68:71], v[112:115], 0
	v_exp_f32_e32 v48, v48
	v_exp_f32_e32 v49, v49
	v_exp_f32_e32 v50, v50
	v_exp_f32_e32 v51, v51
	v_mfma_f32_32x32x16_bf16 v[80:95], v[168:171], v[96:99], v[80:95]
	v_exp_f32_e32 v52, v52
	v_exp_f32_e32 v53, v53
	v_exp_f32_e32 v54, v54
	v_exp_f32_e32 v55, v55
	s_waitcnt lgkmcnt(11)
	v_mfma_f32_32x32x16_bf16 v[64:79], v[172:175], v[96:99], v[64:79]
	ds_read_b128 v[168:171], v165 offset:13440
	ds_read_b128 v[172:175], v165 offset:13472
	ds_read_b128 v[192:195], v165 offset:20096
	ds_read_b128 v[196:199], v165 offset:20128
	v_cvt_pk_bf16_f32 v152, v48, v49
	v_cvt_pk_bf16_f32 v153, v50, v51
	v_cvt_pk_bf16_f32 v154, v52, v53
	v_cvt_pk_bf16_f32 v155, v54, v55
	v_add_f32_e32 v230, 0, v48
	v_add_f32_e32 v230, v49, v230
	v_add_f32_e32 v230, v50, v230
	v_add_f32_e32 v230, v51, v230
	v_add_f32_e32 v230, v52, v230
	v_add_f32_e32 v230, v53, v230
	v_add_f32_e32 v230, v54, v230
	v_add_f32_e32 v230, v55, v230
	s_waitcnt lgkmcnt(14)
	v_mfma_f32_32x32x16_bf16 v[80:95], v[176:179], v[100:103], v[80:95]
	ds_read2_b64 a[0:3], v241 offset0:44 offset1:46
	s_waitcnt lgkmcnt(13)
	v_mfma_f32_32x32x16_bf16 v[64:79], v[184:187], v[100:103], v[64:79]
	v_exp_f32_e32 v56, v56
	v_exp_f32_e32 v57, v57
	v_exp_f32_e32 v58, v58
	v_exp_f32_e32 v59, v59
	v_mfma_f32_32x32x16_bf16 v[80:95], v[180:183], v[104:107], v[80:95]
	v_exp_f32_e32 v60, v60
	v_exp_f32_e32 v61, v61
	v_exp_f32_e32 v62, v62
	v_exp_f32_e32 v63, v63
	s_waitcnt lgkmcnt(12)
	v_mfma_f32_32x32x16_bf16 v[64:79], v[188:191], v[104:107], v[64:79]
	s_waitcnt lgkmcnt(10)
	v_mfma_f32_32x32x16_bf16 v[16:31], v[206:209], v[152:155], v[16:31]
	v_cvt_pk_bf16_f32 v48, v56, v57
	v_cvt_pk_bf16_f32 v49, v58, v59
	v_cvt_pk_bf16_f32 v50, v60, v61
	v_cvt_pk_bf16_f32 v51, v62, v63
	v_mfma_f32_32x32x16_bf16 v[0:15], v[210:213], v[152:155], v[0:15]
	v_add_f32_e32 v230, v56, v230
	v_add_f32_e32 v230, v57, v230
	v_add_f32_e32 v230, v58, v230
	v_add_f32_e32 v230, v59, v230
	v_add_f32_e32 v230, v60, v230
	v_add_f32_e32 v230, v61, v230
	v_add_f32_e32 v230, v62, v230
	v_add_f32_e32 v230, v63, v230
	s_waitcnt lgkmcnt(4)
	v_mfma_f32_32x32x16_bf16 v[80:95], v[168:171], v[108:111], v[80:95]
	v_mfma_f32_32x32x16_bf16 v[16:31], v[214:217], v[48:51], v[16:31]
	v_exp_f32_e32 v32, v32
	v_exp_f32_e32 v33, v33
	v_exp_f32_e32 v34, v34
	v_exp_f32_e32 v35, v35
	v_mfma_f32_32x32x16_bf16 v[0:15], v[218:221], v[48:51], v[0:15]
	v_exp_f32_e32 v36, v36
	v_exp_f32_e32 v37, v37
	v_exp_f32_e32 v38, v38
	v_exp_f32_e32 v39, v39
	s_waitcnt lgkmcnt(2)
	v_mfma_f32_32x32x16_bf16 v[64:79], v[192:195], v[108:111], v[64:79]
	v_cvt_pk_bf16_f32 v152, v32, v33
	v_cvt_pk_bf16_f32 v153, v34, v35
	v_cvt_pk_bf16_f32 v154, v36, v37
	v_cvt_pk_bf16_f32 v155, v38, v39
	v_mfma_f32_32x32x16_bf16 v[80:95], v[172:175], v[116:119], v[80:95]
	v_add_f32_e32 v230, v32, v230
	v_add_f32_e32 v230, v33, v230
	v_add_f32_e32 v230, v34, v230
	v_add_f32_e32 v230, v35, v230
	v_add_f32_e32 v230, v36, v230
	v_add_f32_e32 v230, v37, v230
	v_add_f32_e32 v230, v38, v230
	v_add_f32_e32 v230, v39, v230
	s_waitcnt lgkmcnt(1)
	v_mfma_f32_32x32x16_bf16 v[64:79], v[196:199], v[116:119], v[64:79]
	v_mfma_f32_32x32x16_bf16 v[16:31], v[222:225], v[152:155], v[16:31]
	v_exp_f32_e32 v40, v40
	v_exp_f32_e32 v41, v41
	v_exp_f32_e32 v42, v42
	v_exp_f32_e32 v43, v43
	v_mfma_f32_32x32x16_bf16 v[0:15], v[226:229], v[152:155], v[0:15]
	v_exp_f32_e32 v44, v44
	v_exp_f32_e32 v45, v45
	v_exp_f32_e32 v46, v46
	v_exp_f32_e32 v47, v47
	v_cvt_pk_bf16_f32 v48, v40, v41
	v_cvt_pk_bf16_f32 v49, v42, v43
	v_cvt_pk_bf16_f32 v50, v44, v45
	v_cvt_pk_bf16_f32 v51, v46, v47
	v_add_f32_e32 v230, v40, v230
	v_add_f32_e32 v230, v41, v230
	v_add_f32_e32 v230, v42, v230
	v_add_f32_e32 v230, v43, v230
	v_add_f32_e32 v230, v44, v230
	v_add_f32_e32 v230, v45, v230
	v_add_f32_e32 v230, v46, v230
	v_add_f32_e32 v230, v47, v230
	v_add_f32_e32 v167, v167, v230
	s_waitcnt lgkmcnt(0)
	v_mfma_f32_32x32x16_bf16 v[0:15], v[236:239], v[48:51], v[0:15]
	v_mfma_f32_32x32x16_bf16 v[16:31], a[0:3], v[48:51], v[16:31]
.Latt_e_nors_join:
	s_not_b64 s[8:9], s[10:11]
	s_andn2_b64 vcc, exec, s[10:11]
	s_cbranch_vccnz .LBB0_443
	s_waitcnt vmcnt(2)
	ds_write_b128 v162, v[120:123]
	s_and_saveexec_b64 s[2:3], s[6:7]
	s_cbranch_execz .LBB0_442
	s_waitcnt vmcnt(1)
	ds_write_b128 v164, v[124:127] offset:128

; #define LAS __attribute__((address_space(3)))
; __device__ __forceinline__ float shx32(float v, int lane) { return __int_as_float(__builtin_amdgcn_ds_bpermute((lane ^ 32) << 2, __float_as_int(v))); }
; __device__ __forceinline__ float fexp2(float x) { return __builtin_amdgcn_exp2f(x); }
; __device__ __forceinline__ float max3f(float a, float b, float c) { float d; asm("v_max3_f32 %0, %1, %2, %3" : "=v"(d) : "v"(a), "v"(b), "v"(c)); return d; }
; #define ATT_LOADK(rk, rr, kt_) do { if (MODE == 3 && (kt_) > 1) break; rk = *(const u32x4*)(gkn + (size_t)(kt_) * 64 * 512); rr = *(const u32x4*)(gkr + (size_t)(kt_) * 64 * 32); } while (0)
; #define ATT_LOADV(rv, kt_) do { if (MODE == 3 && (kt_) > 1) break; rv = *(const u32x4*)(gvt + (size_t)(kt_) * 64); } while (0)
; #define ATT_WRITEK(rk, rr, buf) do { LAS unsigned char* nb_ = lds + (buf) * KBUF; *(LAS u32x4*)(nb_ + skn) = rk; if (tid < 256) *(LAS u32x4*)(nb_ + skr) = rr; } while (0)
; template <int MODE>
; __device__ __forceinline__ void attn_pv(const LAS unsigned char* vb_, f32x16 (&st)[2], f32x16 (&ot)[2], float& mrun, float& lsum, const int ql, const int hf, const int lane) {
;     if (MODE != 1) {
;     float mx = max3f(st[0][0], st[1][0], st[0][1]), my = max3f(st[1][1], st[0][2], st[1][2]);
; #pragma unroll
;     for (int i = 3; i < 15; i += 2) { mx = max3f(mx, st[0][i], st[1][i]); my = max3f(my, st[0][i + 1], st[1][i + 1]); }
;     mx = max3f(mx, st[0][15], st[1][15]); mx = max3f(mx, my, my);
;     if (__builtin_amdgcn_ballot_w64(mx > mrun + 8.0f) != 0ull) {
;         mx = fmaxf(mx, shx32(mx, lane));
;         const float mnew = (mx > mrun + 8.0f) ? mx : mrun;
;         const float alpha = fexp2(mrun - mnew);
;         mrun = mnew; lsum *= alpha;
; #pragma unroll
;         for (int i = 0; i < 16; ++i) { ot[0][i] *= alpha; ot[1][i] *= alpha; }
;     }
; template <int MODE>
; __device__ __forceinline__ void attn_phase(const Args& a, bool do_ctx, LAS unsigned char* lds, const int wid_s) {
;     ...
;             if (t + 2 < nkt) ATT_WRITEK(kK, kR, 0);
;             ATT_WRITEV(vV, 1);
;             __syncthreads();
;             if (t + 3 < nkt) ATT_LOADK(kK, kR, t + 3);
;             if (t + 2 < nkt) ATT_LOADV(vV, t + 2);
;             if (t + 2 < nkt) attn_qk<MODE>(lds, qf, sa, ql, hf);
;             __builtin_amdgcn_sched_barrier(0);
;             attn_pv<MODE>(ldsv + VBUF, sb, ot, mrun, lsum, ql, hf, lane);
.LBB0_443:
	s_mov_b32 s2, 0x8a00
	s_cmp_lt_u32 s12, s25
	v_add3_u32 v32, v162, v161, s2
	s_cselect_b64 s[10:11], -1, 0
	s_cmp_ge_u32 s12, s25
	s_waitcnt vmcnt(0)
	ds_write2_b64 v32, v[128:129], v[130:131] offset1:1
	s_waitcnt lgkmcnt(0)
	s_barrier
	s_cbranch_scc1 .Latt_o_noK
	s_add_u32 s86, s80, 0x10000
	s_addc_u32 s87, s81, 0
	s_add_u32 s88, s82, 0x1000
	s_addc_u32 s89, s83, 0
	global_load_dwordx4 v[120:123], v146, s[86:87]
	global_load_dwordx4 v[124:127], v148, s[88:89]
.Latt_o_noK:
	s_and_b64 vcc, exec, s[8:9]
	s_cbranch_vccnz .Latt_o_tail
	global_load_dwordx4 v[128:131], v150, s[84:85] offset:256
	ds_read_b128 v[32:35], v165
	ds_read_b128 v[152:155], v165 offset:32
	ds_read_b128 v[36:39], v165 offset:6656
	ds_read_b128 v[206:209], v165 offset:6688
	ds_read_b128 v[210:213], v165 offset:64
	ds_read_b128 v[214:217], v165 offset:96
	ds_read_b128 v[218:221], v165 offset:6720
	ds_read_b128 v[222:225], v165 offset:6752
	ds_read2_b64 v[176:179], v242 offset0:64 offset1:66
	ds_read2_b64 v[180:183], v243 offset0:96 offset1:98
	ds_read2_b64 v[184:187], v242 offset0:68 offset1:70
	ds_read2_b64 v[188:191], v243 offset0:100 offset1:102
	ds_read2_b64 v[192:195], v242 offset0:72 offset1:74
	ds_read2_b64 v[196:199], v243 offset0:104 offset1:106
	ds_read2_b64 v[172:175], v242 offset0:76 offset1:78
	v_max3_f32 v156, v80, v64, v81
	v_max3_f32 v157, v65, v82, v66
	v_max3_f32 v156, v156, v83, v67
	v_max3_f32 v157, v157, v84, v68
	v_max3_f32 v156, v156, v85, v69
	v_max3_f32 v157, v157, v86, v70
	v_max3_f32 v156, v156, v87, v71
	v_max3_f32 v157, v157, v88, v72
	v_max3_f32 v156, v156, v89, v73
	v_max3_f32 v157, v157, v90, v74
	v_max3_f32 v156, v156, v91, v75
	v_max3_f32 v157, v157, v92, v76
	v_max3_f32 v156, v156, v93, v77
	v_max3_f32 v157, v157, v94, v78
	v_max3_f32 v156, v156, v95, v79
	v_max3_f32 v157, v156, v157, v157
	v_add_f32_e32 v156, 0x41000000, v143
	v_cmp_gt_f32_e32 vcc, v157, v156
	s_cbranch_vccz .Latt_o_nors
	ds_bpermute_b32 v231, v163, v157
	v_max_f32_e32 v157, v157, v157
	s_waitcnt lgkmcnt(0)
	v_max_f32_e32 v231, v231, v231
	v_max_f32_e32 v157, v157, v231
	v_cmp_gt_f32_e32 vcc, v157, v156
	s_nop 1
	v_cndmask_b32_e32 v157, v143, v157, vcc
	v_add_f32_e32 v231, 0x41400000, v157
	s_mov_b32 s2, 0x41a00000
	v_cmp_le_f32_e64 vcc, |v231|, s2
	s_nop 1
	v_cndmask_b32_e32 v157, v157, v201, vcc
	v_sub_f32_e32 v143, v143, v157
	v_exp_f32_e32 v156, v143
	v_mov_b32_e32 v143, v157
	v_mul_f32_e32 v167, v167, v156
	v_pk_mul_f32 v[14:15], v[14:15], v[156:157] op_sel_hi:[1,0]
	v_pk_mul_f32 v[12:13], v[12:13], v[156:157] op_sel_hi:[1,0]
	v_pk_mul_f32 v[10:11], v[10:11], v[156:157] op_sel_hi:[1,0]
	v_pk_mul_f32 v[8:9], v[8:9], v[156:157] op_sel_hi:[1,0]
	v_pk_mul_f32 v[6:7], v[6:7], v[156:157] op_sel_hi:[1,0]
	v_pk_mul_f32 v[4:5], v[4:5], v[156:157] op_sel_hi:[1,0]
	v_pk_mul_f32 v[2:3], v[2:3], v[156:157] op_sel_hi:[1,0]
	v_pk_mul_f32 v[0:1], v[0:1], v[156:157] op_sel_hi:[1,0]
	v_pk_mul_f32 v[30:31], v[30:31], v[156:157] op_sel_hi:[1,0]
	v_pk_mul_f32 v[28:29], v[28:29], v[156:157] op_sel_hi:[1,0]
	v_pk_mul_f32 v[26:27], v[26:27], v[156:157] op_sel_hi:[1,0]
	v_pk_mul_f32 v[24:25], v[24:25], v[156:157] op_sel_hi:[1,0]
	v_pk_mul_f32 v[22:23], v[22:23], v[156:157] op_sel_hi:[1,0]
	v_pk_mul_f32 v[20:21], v[20:21], v[156:157] op_sel_hi:[1,0]
	v_pk_mul_f32 v[18:19], v[18:19], v[156:157] op_sel_hi:[1,0]
	v_pk_mul_f32 v[16:17], v[16:17], v[156:157] op_sel_hi:[1,0]
	v_cmp_neq_f32_e32 vcc, 0, v143
	s_nop 1
	s_cmp_eq_u64 vcc, 0
	s_cselect_b32 s90, 1, 0
.Latt_o_nors:
	s_cmp_lg_u32 s90, 0
	s_cbranch_scc1 .Latt_o_nors_fast
	s_waitcnt lgkmcnt(14)
	v_mfma_f32_32x32x16_bf16 v[48:63], v[32:35], v[112:115], 0
	v_sub_f32_e32 v80, v80, v143
	v_sub_f32_e32 v81, v81, v143
	v_sub_f32_e32 v82, v82, v143
	v_sub_f32_e32 v83, v83, v143
	v_sub_f32_e32 v84, v84, v143
	v_sub_f32_e32 v85, v85, v143
	v_sub_f32_e32 v86, v86, v143
	v_sub_f32_e32 v87, v87, v143
	s_waitcnt lgkmcnt(12)
	v_mfma_f32_32x32x16_bf16 v[32:47], v[36:39], v[112:115], 0
	v_exp_f32_e32 v80, v80
	v_exp_f32_e32 v81, v81
	v_exp_f32_e32 v82, v82
	v_exp_f32_e32 v83, v83
	v_mfma_f32_32x32x16_bf16 v[48:63], v[152:155], v[96:99], v[48:63]
	v_exp_f32_e32 v84, v84
	v_exp_f32_e32 v85, v85
	v_exp_f32_e32 v86, v86
	v_exp_f32_e32 v87, v87
	s_waitcnt lgkmcnt(11)
	v_mfma_f32_32x32x16_bf16 v[32:47], v[206:209], v[96:99], v[32:47]
	ds_read_b128 v[152:155], v165 offset:128
	ds_read_b128 v[206:209], v165 offset:160
	ds_read_b128 v[226:229], v165 offset:6784
	ds_read_b128 v[236:239], v165 offset:6816
	v_cvt_pk_bf16_f32 v168, v80, v81
	v_cvt_pk_bf16_f32 v169, v82, v83
	v_cvt_pk_bf16_f32 v170, v84, v85
	v_cvt_pk_bf16_f32 v171, v86, v87
	v_add_f32_e32 v230, 0, v80
	v_add_f32_e32 v230, v81, v230
	v_add_f32_e32 v230, v82, v230
	v_add_f32_e32 v230, v83, v230
	v_add_f32_e32 v230, v84, v230
	v_add_f32_e32 v230, v85, v230
	v_add_f32_e32 v230, v86, v230
	v_add_f32_e32 v230, v87, v230
	s_waitcnt lgkmcnt(14)
	v_mfma_f32_32x32x16_bf16 v[48:63], v[210:213], v[100:103], v[48:63]
	ds_read2_b64 a[0:3], v243 offset0:108 offset1:110
	v_sub_f32_e32 v88, v88, v143
	v_sub_f32_e32 v89, v89, v143
	v_sub_f32_e32 v90, v90, v143
	v_sub_f32_e32 v91, v91, v143
	v_sub_f32_e32 v92, v92, v143
	v_sub_f32_e32 v93, v93, v143
	v_sub_f32_e32 v94, v94, v143
	v_sub_f32_e32 v95, v95, v143
	s_waitcnt lgkmcnt(13)
	v_mfma_f32_32x32x16_bf16 v[32:47], v[218:221], v[100:103], v[32:47]
	v_exp_f32_e32 v88, v88
	v_exp_f32_e32 v89, v89
	v_exp_f32_e32 v90, v90
	v_exp_f32_e32 v91, v91
	v_mfma_f32_32x32x16_bf16 v[48:63], v[214:217], v[104:107], v[48:63]
	v_exp_f32_e32 v92, v92
	v_exp_f32_e32 v93, v93
	v_exp_f32_e32 v94, v94
	v_exp_f32_e32 v95, v95
	s_waitcnt lgkmcnt(12)
; #define LAS __attribute__((address_space(3)))
; #define ATT_MMA(a_, b_, c_, x_, y_, z_) att_mma<MODE>(a_, b_, c_)
; template <int MODE>
; __device__ __forceinline__ void attn_qk(const LAS unsigned char* kb_, const bf16x8 (&qf)[6], f32x16 (&st)[2], const int ql, const int hf) {
;     ...
;     bf16x8 ka[4], kc[4], ke[4];
; #pragma unroll
;     for (int s = 0; s < 2; ++s) { ka[2 * s] = ATT_KF(0, s); ka[2 * s + 1] = ATT_KF(1, s); }
; #pragma unroll
;     for (int s = 2; s < 4; ++s) { kc[2 * (s - 2)] = ATT_KF(0, s); kc[2 * (s - 2) + 1] = ATT_KF(1, s); }
;     __builtin_amdgcn_sched_barrier(0);
; #pragma unroll
;     for (int i = 0; i < 16; ++i) { st[0][i] = 0.f; st[1][i] = 0.f; }
; #pragma unroll
;     for (int s = 0; s < 2; ++s) { st[0] = ATT_MMA(ka[2 * s], qf[s], st[0], 0, 0, 0); st[1] = ATT_MMA(ka[2 * s + 1], qf[s], st[1], 0, 0, 0); }
;     __builtin_amdgcn_sched_barrier(0);
; #pragma unroll
;     for (int s = 4; s < 6; ++s) { ke[2 * (s - 4)] = ATT_KF(0, s); ke[2 * (s - 4) + 1] = ATT_KF(1, s); }
;     __builtin_amdgcn_sched_barrier(0);
; #pragma unroll
; template <int MODE>
; __device__ __forceinline__ void attn_pv(const LAS unsigned char* vb_, f32x16 (&st)[2], f32x16 (&ot)[2], float& mrun, float& lsum, const int ql, const int hf, const int lane) {
;     ...
;     float ps = 0.f;
; #pragma unroll
;     for (int kb = 0; kb < 2; ++kb)
; #pragma unroll
;         for (int i = 0; i < 16; ++i) { const float p = fexp2(st[kb][i] - mrun); st[kb][i] = p; ps += p; }
;     lsum += ps;
;     } else lsum += st[0][0];
; #pragma unroll
;     for (int kb = 0; kb < 2; ++kb)
; #pragma unroll
;         for (int sI = 0; sI < 2; ++sI) {
;             u32x4 pw = {pk_bf16(st[kb][8 * sI + 0], st[kb][8 * sI + 1]), pk_bf16(st[kb][8 * sI + 2], st[kb][8 * sI + 3]),
;                         pk_bf16(st[kb][8 * sI + 4], st[kb][8 * sI + 5]), pk_bf16(st[kb][8 * sI + 6], st[kb][8 * sI + 7])};
;             const bf16x8 pf = __builtin_bit_cast(bf16x8, pw);
; #pragma unroll
;             for (int db = 0; db < 2; ++db) {
;                 const LAS unsigned char* vp = vb_ + (db * 32 + ql) * VROW + (kb * 32 + 16 * sI + 4 * hf) * 2;
;                 const u32x2 v0 = *(const LAS u32x2*)vp, v1 = *(const LAS u32x2*)(vp + 16);
;                 u32x4 vw = {v0[0], v0[1], v1[0], v1[1]};
;                 ot[db] = att_mma<MODE>(__builtin_bit_cast(bf16x8, vw), pf, ot[db]);
;             }
;         }
; }
	v_mfma_f32_32x32x16_bf16 v[32:47], v[222:225], v[104:107], v[32:47]
	s_waitcnt lgkmcnt(10)
	v_mfma_f32_32x32x16_bf16 v[0:15], v[176:179], v[168:171], v[0:15]
	v_cvt_pk_bf16_f32 v80, v88, v89
	v_cvt_pk_bf16_f32 v81, v90, v91
	v_cvt_pk_bf16_f32 v82, v92, v93
	v_cvt_pk_bf16_f32 v83, v94, v95
	v_mfma_f32_32x32x16_bf16 v[16:31], v[180:183], v[168:171], v[16:31]
	v_add_f32_e32 v230, v88, v230
	v_add_f32_e32 v230, v89, v230
	v_add_f32_e32 v230, v90, v230
	v_add_f32_e32 v230, v91, v230
	v_add_f32_e32 v230, v92, v230
	v_add_f32_e32 v230, v93, v230
	v_add_f32_e32 v230, v94, v230
	v_add_f32_e32 v230, v95, v230
	s_waitcnt lgkmcnt(4)
	v_mfma_f32_32x32x16_bf16 v[48:63], v[152:155], v[108:111], v[48:63]
	v_sub_f32_e32 v64, v64, v143
	v_sub_f32_e32 v65, v65, v143
	v_sub_f32_e32 v66, v66, v143
	v_sub_f32_e32 v67, v67, v143
	v_sub_f32_e32 v68, v68, v143
	v_sub_f32_e32 v69, v69, v143
	v_sub_f32_e32 v70, v70, v143
	v_sub_f32_e32 v71, v71, v143
	v_mfma_f32_32x32x16_bf16 v[0:15], v[184:187], v[80:83], v[0:15]
	v_exp_f32_e32 v64, v64
	v_exp_f32_e32 v65, v65
	v_exp_f32_e32 v66, v66
	v_exp_f32_e32 v67, v67
	v_mfma_f32_32x32x16_bf16 v[16:31], v[188:191], v[80:83], v[16:31]
	v_exp_f32_e32 v68, v68
	v_exp_f32_e32 v69, v69
	v_exp_f32_e32 v70, v70
	v_exp_f32_e32 v71, v71
	s_waitcnt lgkmcnt(2)
	v_mfma_f32_32x32x16_bf16 v[32:47], v[226:229], v[108:111], v[32:47]
	v_cvt_pk_bf16_f32 v168, v64, v65
	v_cvt_pk_bf16_f32 v169, v66, v67
	v_cvt_pk_bf16_f32 v170, v68, v69
	v_cvt_pk_bf16_f32 v171, v70, v71
	v_mfma_f32_32x32x16_bf16 v[48:63], v[206:209], v[116:119], v[48:63]
	v_add_f32_e32 v230, v64, v230
	v_add_f32_e32 v230, v65, v230
	v_add_f32_e32 v230, v66, v230
	v_add_f32_e32 v230, v67, v230
	v_add_f32_e32 v230, v68, v230
	v_add_f32_e32 v230, v69, v230
	v_add_f32_e32 v230, v70, v230
	v_add_f32_e32 v230, v71, v230
	s_waitcnt lgkmcnt(1)
	v_mfma_f32_32x32x16_bf16 v[32:47], v[236:239], v[116:119], v[32:47]
	v_sub_f32_e32 v72, v72, v143
	v_sub_f32_e32 v73, v73, v143
	v_sub_f32_e32 v74, v74, v143
	v_sub_f32_e32 v75, v75, v143
	v_sub_f32_e32 v76, v76, v143
	v_sub_f32_e32 v77, v77, v143
	v_sub_f32_e32 v78, v78, v143
	v_sub_f32_e32 v79, v79, v143
	v_mfma_f32_32x32x16_bf16 v[0:15], v[192:195], v[168:171], v[0:15]
	v_exp_f32_e32 v72, v72
	v_exp_f32_e32 v73, v73
	v_exp_f32_e32 v74, v74
	v_exp_f32_e32 v75, v75
	v_mfma_f32_32x32x16_bf16 v[16:31], v[196:199], v[168:171], v[16:31]
	v_exp_f32_e32 v76, v76
	v_exp_f32_e32 v77, v77
	v_exp_f32_e32 v78, v78
	v_exp_f32_e32 v79, v79
	v_cvt_pk_bf16_f32 v80, v72, v73
	v_cvt_pk_bf16_f32 v81, v74, v75
	v_cvt_pk_bf16_f32 v82, v76, v77
	v_cvt_pk_bf16_f32 v83, v78, v79
	v_add_f32_e32 v230, v72, v230
	v_add_f32_e32 v230, v73, v230
	v_add_f32_e32 v230, v74, v230
	v_add_f32_e32 v230, v75, v230
	v_add_f32_e32 v230, v76, v230
	v_add_f32_e32 v230, v77, v230
	v_add_f32_e32 v230, v78, v230
	v_add_f32_e32 v230, v79, v230
	v_add_f32_e32 v167, v167, v230
	s_waitcnt lgkmcnt(0)
	v_mfma_f32_32x32x16_bf16 v[0:15], v[172:175], v[80:83], v[0:15]
	v_mfma_f32_32x32x16_bf16 v[16:31], a[0:3], v[80:83], v[16:31]
	s_branch .Latt_o_nors_join
; #define LAS __attribute__((address_space(3)))
; #define ATT_MMA(a_, b_, c_, x_, y_, z_) att_mma<MODE>(a_, b_, c_)
; template <int MODE>
; __device__ __forceinline__ void attn_qk(const LAS unsigned char* kb_, const bf16x8 (&qf)[6], f32x16 (&st)[2], const int ql, const int hf) {
;     ...
;     bf16x8 ka[4], kc[4], ke[4];
; #pragma unroll
;     for (int s = 0; s < 2; ++s) { ka[2 * s] = ATT_KF(0, s); ka[2 * s + 1] = ATT_KF(1, s); }
; #pragma unroll
;     for (int s = 2; s < 4; ++s) { kc[2 * (s - 2)] = ATT_KF(0, s); kc[2 * (s - 2) + 1] = ATT_KF(1, s); }
;     __builtin_amdgcn_sched_barrier(0);
; #pragma unroll
;     for (int i = 0; i < 16; ++i) { st[0][i] = 0.f; st[1][i] = 0.f; }
; #pragma unroll
;     for (int s = 0; s < 2; ++s) { st[0] = ATT_MMA(ka[2 * s], qf[s], st[0], 0, 0, 0); st[1] = ATT_MMA(ka[2 * s + 1], qf[s], st[1], 0, 0, 0); }
;     __builtin_amdgcn_sched_barrier(0);
; #pragma unroll
;     for (int s = 4; s < 6; ++s) { ke[2 * (s - 4)] = ATT_KF(0, s); ke[2 * (s - 4) + 1] = ATT_KF(1, s); }
;     __builtin_amdgcn_sched_barrier(0);
; #pragma unroll
; template <int MODE>
; __device__ __forceinline__ void attn_pv(const LAS unsigned char* vb_, f32x16 (&st)[2], f32x16 (&ot)[2], float& mrun, float& lsum, const int ql, const int hf, const int lane) {
;     ...
;     float ps = 0.f;
; #pragma unroll
;     for (int kb = 0; kb < 2; ++kb)
; #pragma unroll
;         for (int i = 0; i < 16; ++i) { const float p = fexp2(st[kb][i] - mrun); st[kb][i] = p; ps += p; }
;     lsum += ps;
;     } else lsum += st[0][0];
; #pragma unroll
;     for (int kb = 0; kb < 2; ++kb)
; #pragma unroll
;         for (int sI = 0; sI < 2; ++sI) {
;             u32x4 pw = {pk_bf16(st[kb][8 * sI + 0], st[kb][8 * sI + 1]), pk_bf16(st[kb][8 * sI + 2], st[kb][8 * sI + 3]),
;                         pk_bf16(st[kb][8 * sI + 4], st[kb][8 * sI + 5]), pk_bf16(st[kb][8 * sI + 6], st[kb][8 * sI + 7])};
;             const bf16x8 pf = __builtin_bit_cast(bf16x8, pw);
; #pragma unroll
;             for (int db = 0; db < 2; ++db) {
;                 const LAS unsigned char* vp = vb_ + (db * 32 + ql) * VROW + (kb * 32 + 16 * sI + 4 * hf) * 2;
;                 const u32x2 v0 = *(const LAS u32x2*)vp, v1 = *(const LAS u32x2*)(vp + 16);
;                 u32x4 vw = {v0[0], v0[1], v1[0], v1[1]};
;                 ot[db] = att_mma<MODE>(__builtin_bit_cast(bf16x8, vw), pf, ot[db]);
;             }
;         }
; }
.Latt_o_nors_fast:
	s_waitcnt lgkmcnt(14)
	v_mfma_f32_32x32x16_bf16 v[48:63], v[32:35], v[112:115], 0
	s_waitcnt lgkmcnt(12)
	v_mfma_f32_32x32x16_bf16 v[32:47], v[36:39], v[112:115], 0
	v_exp_f32_e32 v80, v80
	v_exp_f32_e32 v81, v81
	v_exp_f32_e32 v82, v82
	v_exp_f32_e32 v83, v83
	v_mfma_f32_32x32x16_bf16 v[48:63], v[152:155], v[96:99], v[48:63]
	v_exp_f32_e32 v84, v84
	v_exp_f32_e32 v85, v85
	v_exp_f32_e32 v86, v86
	v_exp_f32_e32 v87, v87
	s_waitcnt lgkmcnt(11)
	v_mfma_f32_32x32x16_bf16 v[32:47], v[206:209], v[96:99], v[32:47]
	ds_read_b128 v[152:155], v165 offset:128
	ds_read_b128 v[206:209], v165 offset:160
	ds_read_b128 v[226:229], v165 offset:6784
	ds_read_b128 v[236:239], v165 offset:6816
	v_cvt_pk_bf16_f32 v168, v80, v81
	v_cvt_pk_bf16_f32 v169, v82, v83
	v_cvt_pk_bf16_f32 v170, v84, v85
	v_cvt_pk_bf16_f32 v171, v86, v87
	v_add_f32_e32 v230, 0, v80
	v_add_f32_e32 v230, v81, v230
	v_add_f32_e32 v230, v82, v230
	v_add_f32_e32 v230, v83, v230
	v_add_f32_e32 v230, v84, v230
	v_add_f32_e32 v230, v85, v230
	v_add_f32_e32 v230, v86, v230
	v_add_f32_e32 v230, v87, v230
	s_waitcnt lgkmcnt(14)
	v_mfma_f32_32x32x16_bf16 v[48:63], v[210:213], v[100:103], v[48:63]
	ds_read2_b64 a[0:3], v243 offset0:108 offset1:110
	s_waitcnt lgkmcnt(13)
	v_mfma_f32_32x32x16_bf16 v[32:47], v[218:221], v[100:103], v[32:47]
	v_exp_f32_e32 v88, v88
	v_exp_f32_e32 v89, v89
	v_exp_f32_e32 v90, v90
	v_exp_f32_e32 v91, v91
	v_mfma_f32_32x32x16_bf16 v[48:63], v[214:217], v[104:107], v[48:63]
	v_exp_f32_e32 v92, v92
	v_exp_f32_e32 v93, v93
	v_exp_f32_e32 v94, v94
	v_exp_f32_e32 v95, v95
	s_waitcnt lgkmcnt(12)
	v_mfma_f32_32x32x16_bf16 v[32:47], v[222:225], v[104:107], v[32:47]
	s_waitcnt lgkmcnt(10)
	v_mfma_f32_32x32x16_bf16 v[0:15], v[176:179], v[168:171], v[0:15]
	v_cvt_pk_bf16_f32 v80, v88, v89
	v_cvt_pk_bf16_f32 v81, v90, v91
	v_cvt_pk_bf16_f32 v82, v92, v93
	v_cvt_pk_bf16_f32 v83, v94, v95
	v_mfma_f32_32x32x16_bf16 v[16:31], v[180:183], v[168:171], v[16:31]
	v_add_f32_e32 v230, v88, v230
	v_add_f32_e32 v230, v89, v230
	v_add_f32_e32 v230, v90, v230
	v_add_f32_e32 v230, v91, v230
	v_add_f32_e32 v230, v92, v230
	v_add_f32_e32 v230, v93, v230
	v_add_f32_e32 v230, v94, v230
	v_add_f32_e32 v230, v95, v230
	s_waitcnt lgkmcnt(4)
	v_mfma_f32_32x32x16_bf16 v[48:63], v[152:155], v[108:111], v[48:63]
	v_mfma_f32_32x32x16_bf16 v[0:15], v[184:187], v[80:83], v[0:15]
	v_exp_f32_e32 v64, v64
	v_exp_f32_e32 v65, v65
	v_exp_f32_e32 v66, v66
	v_exp_f32_e32 v67, v67
	v_mfma_f32_32x32x16_bf16 v[16:31], v[188:191], v[80:83], v[16:31]
	v_exp_f32_e32 v68, v68
	v_exp_f32_e32 v69, v69
	v_exp_f32_e32 v70, v70
	v_exp_f32_e32 v71, v71
	s_waitcnt lgkmcnt(2)
	v_mfma_f32_32x32x16_bf16 v[32:47], v[226:229], v[108:111], v[32:47]
	v_cvt_pk_bf16_f32 v168, v64, v65
	v_cvt_pk_bf16_f32 v169, v66, v67
	v_cvt_pk_bf16_f32 v170, v68, v69
	v_cvt_pk_bf16_f32 v171, v70, v71
	v_mfma_f32_32x32x16_bf16 v[48:63], v[206:209], v[116:119], v[48:63]
	v_add_f32_e32 v230, v64, v230
	v_add_f32_e32 v230, v65, v230
	v_add_f32_e32 v230, v66, v230
	v_add_f32_e32 v230, v67, v230
	v_add_f32_e32 v230, v68, v230
	v_add_f32_e32 v230, v69, v230
	v_add_f32_e32 v230, v70, v230
	v_add_f32_e32 v230, v71, v230
	s_waitcnt lgkmcnt(1)
	v_mfma_f32_32x32x16_bf16 v[32:47], v[236:239], v[116:119], v[32:47]
	v_mfma_f32_32x32x16_bf16 v[0:15], v[192:195], v[168:171], v[0:15]
	v_exp_f32_e32 v72, v72
	v_exp_f32_e32 v73, v73
	v_exp_f32_e32 v74, v74
	v_exp_f32_e32 v75, v75
	v_mfma_f32_32x32x16_bf16 v[16:31], v[196:199], v[168:171], v[16:31]
	v_exp_f32_e32 v76, v76
	v_exp_f32_e32 v77, v77
	v_exp_f32_e32 v78, v78
	v_exp_f32_e32 v79, v79
	v_cvt_pk_bf16_f32 v80, v72, v73
	v_cvt_pk_bf16_f32 v81, v74, v75
	v_cvt_pk_bf16_f32 v82, v76, v77
	v_cvt_pk_bf16_f32 v83, v78, v79
	v_add_f32_e32 v230, v72, v230
	v_add_f32_e32 v230, v73, v230
	v_add_f32_e32 v230, v74, v230
	v_add_f32_e32 v230, v75, v230
	v_add_f32_e32 v230, v76, v230
	v_add_f32_e32 v230, v77, v230
	v_add_f32_e32 v230, v78, v230
	v_add_f32_e32 v230, v79, v230
	v_add_f32_e32 v167, v167, v230
	s_waitcnt lgkmcnt(0)
	v_mfma_f32_32x32x16_bf16 v[0:15], v[172:175], v[80:83], v[0:15]
	v_mfma_f32_32x32x16_bf16 v[16:31], a[0:3], v[80:83], v[16:31]

; #define LAS __attribute__((address_space(3)))
; __device__ __forceinline__ float shx32(float v, int lane) { return __int_as_float(__builtin_amdgcn_ds_bpermute((lane ^ 32) << 2, __float_as_int(v))); }
; __device__ __forceinline__ unsigned pk_bf16(float lo, float hi) { unsigned r; asm("v_cvt_pk_bf16_f32 %0, %1, %2" : "=v"(r) : "v"(lo), "v"(hi)); return r; }
; template <int MODE>
; __device__ __forceinline__ void attn_pv(const LAS unsigned char* vb_, f32x16 (&st)[2], f32x16 (&ot)[2], float& mrun, float& lsum, const int ql, const int hf, const int lane) {
;     if (MODE != 1) {
;     float mx = max3f(st[0][0], st[1][0], st[0][1]), my = max3f(st[1][1], st[0][2], st[1][2]);
; #pragma unroll
;     for (int i = 3; i < 15; i += 2) { mx = max3f(mx, st[0][i], st[1][i]); my = max3f(my, st[0][i + 1], st[1][i + 1]); }
;     mx = max3f(mx, st[0][15], st[1][15]); mx = max3f(mx, my, my);
;     if (__builtin_amdgcn_ballot_w64(mx > mrun + 8.0f) != 0ull) {
;         mx = fmaxf(mx, shx32(mx, lane));
;         const float mnew = (mx > mrun + 8.0f) ? mx : mrun;
;         const float alpha = fexp2(mrun - mnew);
;         mrun = mnew; lsum *= alpha;
; #pragma unroll
;         for (int i = 0; i < 16; ++i) { ot[0][i] *= alpha; ot[1][i] *= alpha; }
;     }
;     float ps = 0.f;
; #pragma unroll
;     for (int kb = 0; kb < 2; ++kb)
; #pragma unroll
;         for (int i = 0; i < 16; ++i) { const float p = fexp2(st[kb][i] - mrun); st[kb][i] = p; ps += p; }
;     lsum += ps;
;     } else lsum += st[0][0];
; #pragma unroll
;     for (int kb = 0; kb < 2; ++kb)
; #pragma unroll
;         for (int sI = 0; sI < 2; ++sI) {
;             u32x4 pw = {pk_bf16(st[kb][8 * sI + 0], st[kb][8 * sI + 1]), pk_bf16(st[kb][8 * sI + 2], st[kb][8 * sI + 3]),
;                         pk_bf16(st[kb][8 * sI + 4], st[kb][8 * sI + 5]), pk_bf16(st[kb][8 * sI + 6], st[kb][8 * sI + 7])};
;             const bf16x8 pf = __builtin_bit_cast(bf16x8, pw);
; #pragma unroll
;             for (int db = 0; db < 2; ++db) {
;                 const LAS unsigned char* vp = vb_ + (db * 32 + ql) * VROW + (kb * 32 + 16 * sI + 4 * hf) * 2;
;                 const u32x2 v0 = *(const LAS u32x2*)vp, v1 = *(const LAS u32x2*)(vp + 16);
;                 u32x4 vw = {v0[0], v0[1], v1[0], v1[1]};
;                 ot[db] = att_mma<MODE>(__builtin_bit_cast(bf16x8, vw), pf, ot[db]);
;             }
;         }
; }
.Latt_o_tail:
	ds_read2_b64 v[176:179], v242 offset0:64 offset1:66
	ds_read2_b64 v[180:183], v243 offset0:96 offset1:98
	ds_read2_b64 v[184:187], v242 offset0:68 offset1:70
	ds_read2_b64 v[188:191], v243 offset0:100 offset1:102
	ds_read2_b64 v[192:195], v242 offset0:72 offset1:74
	ds_read2_b64 v[196:199], v243 offset0:104 offset1:106
	ds_read2_b64 v[172:175], v242 offset0:76 offset1:78
	ds_read2_b64 a[0:3], v243 offset0:108 offset1:110
	v_max3_f32 v156, v80, v64, v81
	v_max3_f32 v157, v65, v82, v66
	v_max3_f32 v156, v156, v83, v67
	v_max3_f32 v157, v157, v84, v68
	v_max3_f32 v156, v156, v85, v69
	v_max3_f32 v157, v157, v86, v70
	v_max3_f32 v156, v156, v87, v71
	v_max3_f32 v157, v157, v88, v72
	v_max3_f32 v156, v156, v89, v73
	v_max3_f32 v157, v157, v90, v74
	v_max3_f32 v156, v156, v91, v75
	v_max3_f32 v157, v157, v92, v76
	v_max3_f32 v156, v156, v93, v77
	v_max3_f32 v157, v157, v94, v78
	v_max3_f32 v156, v156, v95, v79
	v_max3_f32 v157, v156, v157, v157
	v_add_f32_e32 v156, 0x41000000, v143
	v_cmp_gt_f32_e32 vcc, v157, v156
	s_cbranch_vccz .Latt_ot_nors
	ds_bpermute_b32 v231, v163, v157
	v_max_f32_e32 v157, v157, v157
	s_waitcnt lgkmcnt(0)
	v_max_f32_e32 v231, v231, v231
	v_max_f32_e32 v157, v157, v231
	v_cmp_gt_f32_e32 vcc, v157, v156
	s_nop 1
	v_cndmask_b32_e32 v157, v143, v157, vcc
	v_add_f32_e32 v231, 0x41400000, v157
	s_mov_b32 s2, 0x41a00000
	v_cmp_le_f32_e64 vcc, |v231|, s2
	s_nop 1
	v_cndmask_b32_e32 v157, v157, v201, vcc
	v_sub_f32_e32 v143, v143, v157
	v_exp_f32_e32 v156, v143
	v_mov_b32_e32 v143, v157
	v_mul_f32_e32 v167, v167, v156
	v_pk_mul_f32 v[14:15], v[14:15], v[156:157] op_sel_hi:[1,0]
	v_pk_mul_f32 v[12:13], v[12:13], v[156:157] op_sel_hi:[1,0]
	v_pk_mul_f32 v[10:11], v[10:11], v[156:157] op_sel_hi:[1,0]
	v_pk_mul_f32 v[8:9], v[8:9], v[156:157] op_sel_hi:[1,0]
	v_pk_mul_f32 v[6:7], v[6:7], v[156:157] op_sel_hi:[1,0]
	v_pk_mul_f32 v[4:5], v[4:5], v[156:157] op_sel_hi:[1,0]
	v_pk_mul_f32 v[2:3], v[2:3], v[156:157] op_sel_hi:[1,0]
	v_pk_mul_f32 v[0:1], v[0:1], v[156:157] op_sel_hi:[1,0]
	v_pk_mul_f32 v[30:31], v[30:31], v[156:157] op_sel_hi:[1,0]
	v_pk_mul_f32 v[28:29], v[28:29], v[156:157] op_sel_hi:[1,0]
	v_pk_mul_f32 v[26:27], v[26:27], v[156:157] op_sel_hi:[1,0]
	v_pk_mul_f32 v[24:25], v[24:25], v[156:157] op_sel_hi:[1,0]
	v_pk_mul_f32 v[22:23], v[22:23], v[156:157] op_sel_hi:[1,0]
	v_pk_mul_f32 v[20:21], v[20:21], v[156:157] op_sel_hi:[1,0]
	v_pk_mul_f32 v[18:19], v[18:19], v[156:157] op_sel_hi:[1,0]
	v_pk_mul_f32 v[16:17], v[16:17], v[156:157] op_sel_hi:[1,0]
	v_cmp_neq_f32_e32 vcc, 0, v143
	s_nop 1
	s_cmp_eq_u64 vcc, 0
	s_cselect_b32 s90, 1, 0
.Latt_ot_nors:
	s_cmp_lg_u32 s90, 0
	s_cbranch_scc1 .Latt_ot_nors_fast
	v_sub_f32_e32 v80, v80, v143
	v_sub_f32_e32 v81, v81, v143
	v_sub_f32_e32 v82, v82, v143
	v_sub_f32_e32 v83, v83, v143
	v_sub_f32_e32 v84, v84, v143
	v_sub_f32_e32 v85, v85, v143
	v_sub_f32_e32 v86, v86, v143
	v_sub_f32_e32 v87, v87, v143
	v_exp_f32_e32 v80, v80
	v_exp_f32_e32 v81, v81
	v_exp_f32_e32 v82, v82
	v_exp_f32_e32 v83, v83
	v_exp_f32_e32 v84, v84
	v_exp_f32_e32 v85, v85
	v_exp_f32_e32 v86, v86
	v_exp_f32_e32 v87, v87
	v_cvt_pk_bf16_f32 v168, v80, v81
	v_cvt_pk_bf16_f32 v169, v82, v83
	v_cvt_pk_bf16_f32 v170, v84, v85
	v_cvt_pk_bf16_f32 v171, v86, v87
	v_add_f32_e32 v230, 0, v80
	v_add_f32_e32 v230, v81, v230
	v_add_f32_e32 v230, v82, v230
	v_add_f32_e32 v230, v83, v230
	v_add_f32_e32 v230, v84, v230
	v_add_f32_e32 v230, v85, v230
	v_add_f32_e32 v230, v86, v230
	v_add_f32_e32 v230, v87, v230
	v_sub_f32_e32 v88, v88, v143
	v_sub_f32_e32 v89, v89, v143
	v_sub_f32_e32 v90, v90, v143
	v_sub_f32_e32 v91, v91, v143
	v_sub_f32_e32 v92, v92, v143
	v_sub_f32_e32 v93, v93, v143
	v_sub_f32_e32 v94, v94, v143
	v_sub_f32_e32 v95, v95, v143
	v_exp_f32_e32 v88, v88
	v_exp_f32_e32 v89, v89
	v_exp_f32_e32 v90, v90
	v_exp_f32_e32 v91, v91
	s_waitcnt lgkmcnt(0)
	v_mfma_f32_32x32x16_bf16 v[0:15], v[176:179], v[168:171], v[0:15]
	v_exp_f32_e32 v92, v92
	v_exp_f32_e32 v93, v93
	v_exp_f32_e32 v94, v94
	v_exp_f32_e32 v95, v95
	v_mfma_f32_32x32x16_bf16 v[16:31], v[180:183], v[168:171], v[16:31]
	v_cvt_pk_bf16_f32 v80, v88, v89
	v_cvt_pk_bf16_f32 v81, v90, v91
	v_cvt_pk_bf16_f32 v82, v92, v93
	v_cvt_pk_bf16_f32 v83, v94, v95
	v_add_f32_e32 v230, v88, v230
	v_add_f32_e32 v230, v89, v230
	v_add_f32_e32 v230, v90, v230
	v_add_f32_e32 v230, v91, v230
	v_add_f32_e32 v230, v92, v230
	v_add_f32_e32 v230, v93, v230
	v_add_f32_e32 v230, v94, v230
	v_add_f32_e32 v230, v95, v230
	v_sub_f32_e32 v64, v64, v143
	v_sub_f32_e32 v65, v65, v143
	v_sub_f32_e32 v66, v66, v143
	v_sub_f32_e32 v67, v67, v143
	v_sub_f32_e32 v68, v68, v143
	v_sub_f32_e32 v69, v69, v143
	v_sub_f32_e32 v70, v70, v143
	v_sub_f32_e32 v71, v71, v143
	v_mfma_f32_32x32x16_bf16 v[0:15], v[184:187], v[80:83], v[0:15]
	v_exp_f32_e32 v64, v64
	v_exp_f32_e32 v65, v65
	v_exp_f32_e32 v66, v66
	v_exp_f32_e32 v67, v67
	v_mfma_f32_32x32x16_bf16 v[16:31], v[188:191], v[80:83], v[16:31]
	v_exp_f32_e32 v68, v68
	v_exp_f32_e32 v69, v69
	v_exp_f32_e32 v70, v70
	v_exp_f32_e32 v71, v71
	v_cvt_pk_bf16_f32 v168, v64, v65
	v_cvt_pk_bf16_f32 v169, v66, v67
	v_cvt_pk_bf16_f32 v170, v68, v69
	v_cvt_pk_bf16_f32 v171, v70, v71
	v_add_f32_e32 v230, v64, v230
	v_add_f32_e32 v230, v65, v230
	v_add_f32_e32 v230, v66, v230
	v_add_f32_e32 v230, v67, v230
	v_add_f32_e32 v230, v68, v230
	v_add_f32_e32 v230, v69, v230
	v_add_f32_e32 v230, v70, v230
	v_add_f32_e32 v230, v71, v230
	v_sub_f32_e32 v72, v72, v143
	v_sub_f32_e32 v73, v73, v143
	v_sub_f32_e32 v74, v74, v143
	v_sub_f32_e32 v75, v75, v143
	v_sub_f32_e32 v76, v76, v143
	v_sub_f32_e32 v77, v77, v143
	v_sub_f32_e32 v78, v78, v143
	v_sub_f32_e32 v79, v79, v143
	v_mfma_f32_32x32x16_bf16 v[0:15], v[192:195], v[168:171], v[0:15]
	v_exp_f32_e32 v72, v72
	v_exp_f32_e32 v73, v73
	v_exp_f32_e32 v74, v74
	v_exp_f32_e32 v75, v75
	v_mfma_f32_32x32x16_bf16 v[16:31], v[196:199], v[168:171], v[16:31]
	v_exp_f32_e32 v76, v76
	v_exp_f32_e32 v77, v77
	v_exp_f32_e32 v78, v78
	v_exp_f32_e32 v79, v79
	v_cvt_pk_bf16_f32 v80, v72, v73
	v_cvt_pk_bf16_f32 v81, v74, v75
	v_cvt_pk_bf16_f32 v82, v76, v77
	v_cvt_pk_bf16_f32 v83, v78, v79
	v_add_f32_e32 v230, v72, v230
	v_add_f32_e32 v230, v73, v230
	v_add_f32_e32 v230, v74, v230
	v_add_f32_e32 v230, v75, v230
	v_add_f32_e32 v230, v76, v230
	v_add_f32_e32 v230, v77, v230
	v_add_f32_e32 v230, v78, v230
	v_add_f32_e32 v230, v79, v230
	v_add_f32_e32 v167, v167, v230
	v_mfma_f32_32x32x16_bf16 v[0:15], v[172:175], v[80:83], v[0:15]
	v_mfma_f32_32x32x16_bf16 v[16:31], a[0:3], v[80:83], v[16:31]
	s_branch .Latt_ot_nors_join
; #define LAS __attribute__((address_space(3)))
; __device__ __forceinline__ unsigned pk_bf16(float lo, float hi) { unsigned r; asm("v_cvt_pk_bf16_f32 %0, %1, %2" : "=v"(r) : "v"(lo), "v"(hi)); return r; }
; __device__ __forceinline__ float fexp2(float x) { return __builtin_amdgcn_exp2f(x); }
; #define ATT_WRITEK(rk, rr, buf) do { LAS unsigned char* nb_ = lds + (buf) * KBUF; *(LAS u32x4*)(nb_ + skn) = rk; if (tid < 256) *(LAS u32x4*)(nb_ + skr) = rr; } while (0)
; #define ATT_WRITEV(rv, buf) do { LAS u32x2* p_ = (LAS u32x2*)(ldsv + (buf) * VBUF + svt); u32x2 lo_ = {rv[0], rv[1]}, hi_ = {rv[2], rv[3]}; p_[0] = lo_; p_[1] = hi_; } while (0)
; template <int MODE>
; __device__ __forceinline__ void attn_pv(const LAS unsigned char* vb_, f32x16 (&st)[2], f32x16 (&ot)[2], float& mrun, float& lsum, const int ql, const int hf, const int lane) {
;     ...
;     float ps = 0.f;
; #pragma unroll
;     for (int kb = 0; kb < 2; ++kb)
; #pragma unroll
;         for (int i = 0; i < 16; ++i) { const float p = fexp2(st[kb][i] - mrun); st[kb][i] = p; ps += p; }
;     lsum += ps;
;     } else lsum += st[0][0];
; #pragma unroll
;     for (int kb = 0; kb < 2; ++kb)
; #pragma unroll
;         for (int sI = 0; sI < 2; ++sI) {
;             u32x4 pw = {pk_bf16(st[kb][8 * sI + 0], st[kb][8 * sI + 1]), pk_bf16(st[kb][8 * sI + 2], st[kb][8 * sI + 3]),
;                         pk_bf16(st[kb][8 * sI + 4], st[kb][8 * sI + 5]), pk_bf16(st[kb][8 * sI + 6], st[kb][8 * sI + 7])};
;             const bf16x8 pf = __builtin_bit_cast(bf16x8, pw);
; #pragma unroll
;             for (int db = 0; db < 2; ++db) {
;                 const LAS unsigned char* vp = vb_ + (db * 32 + ql) * VROW + (kb * 32 + 16 * sI + 4 * hf) * 2;
;                 const u32x2 v0 = *(const LAS u32x2*)vp, v1 = *(const LAS u32x2*)(vp + 16);
;                 u32x4 vw = {v0[0], v0[1], v1[0], v1[1]};
;                 ot[db] = att_mma<MODE>(__builtin_bit_cast(bf16x8, vw), pf, ot[db]);
;             }
;         }
; }
; template <int MODE>
; __device__ __forceinline__ void attn_phase(const Args& a, bool do_ctx, LAS unsigned char* lds, const int wid_s) {
;     ...
;             if (t + 3 < nkt) ATT_WRITEK(kK, kR, 1);
;             if (t + 2 < nkt) ATT_WRITEV(vV, 0);
.Latt_ot_nors_fast:
	v_exp_f32_e32 v80, v80
	v_exp_f32_e32 v81, v81
	v_exp_f32_e32 v82, v82
	v_exp_f32_e32 v83, v83
	v_exp_f32_e32 v84, v84
	v_exp_f32_e32 v85, v85
	v_exp_f32_e32 v86, v86
	v_exp_f32_e32 v87, v87
	v_cvt_pk_bf16_f32 v168, v80, v81
	v_cvt_pk_bf16_f32 v169, v82, v83
	v_cvt_pk_bf16_f32 v170, v84, v85
	v_cvt_pk_bf16_f32 v171, v86, v87
	v_add_f32_e32 v230, 0, v80
	v_add_f32_e32 v230, v81, v230
	v_add_f32_e32 v230, v82, v230
	v_add_f32_e32 v230, v83, v230
	v_add_f32_e32 v230, v84, v230
	v_add_f32_e32 v230, v85, v230
	v_add_f32_e32 v230, v86, v230
	v_add_f32_e32 v230, v87, v230
	v_exp_f32_e32 v88, v88
	v_exp_f32_e32 v89, v89
	v_exp_f32_e32 v90, v90
	v_exp_f32_e32 v91, v91
	s_waitcnt lgkmcnt(0)
	v_mfma_f32_32x32x16_bf16 v[0:15], v[176:179], v[168:171], v[0:15]
	v_exp_f32_e32 v92, v92
	v_exp_f32_e32 v93, v93
	v_exp_f32_e32 v94, v94
	v_exp_f32_e32 v95, v95
	v_mfma_f32_32x32x16_bf16 v[16:31], v[180:183], v[168:171], v[16:31]
	v_cvt_pk_bf16_f32 v80, v88, v89
	v_cvt_pk_bf16_f32 v81, v90, v91
	v_cvt_pk_bf16_f32 v82, v92, v93
	v_cvt_pk_bf16_f32 v83, v94, v95
	v_add_f32_e32 v230, v88, v230
	v_add_f32_e32 v230, v89, v230
	v_add_f32_e32 v230, v90, v230
	v_add_f32_e32 v230, v91, v230
	v_add_f32_e32 v230, v92, v230
	v_add_f32_e32 v230, v93, v230
	v_add_f32_e32 v230, v94, v230
	v_add_f32_e32 v230, v95, v230
	v_mfma_f32_32x32x16_bf16 v[0:15], v[184:187], v[80:83], v[0:15]
	v_exp_f32_e32 v64, v64
	v_exp_f32_e32 v65, v65
	v_exp_f32_e32 v66, v66
	v_exp_f32_e32 v67, v67
	v_mfma_f32_32x32x16_bf16 v[16:31], v[188:191], v[80:83], v[16:31]
	v_exp_f32_e32 v68, v68
	v_exp_f32_e32 v69, v69
	v_exp_f32_e32 v70, v70
	v_exp_f32_e32 v71, v71
	v_cvt_pk_bf16_f32 v168, v64, v65
	v_cvt_pk_bf16_f32 v169, v66, v67
	v_cvt_pk_bf16_f32 v170, v68, v69
	v_cvt_pk_bf16_f32 v171, v70, v71
	v_add_f32_e32 v230, v64, v230
	v_add_f32_e32 v230, v65, v230
	v_add_f32_e32 v230, v66, v230
	v_add_f32_e32 v230, v67, v230
	v_add_f32_e32 v230, v68, v230
	v_add_f32_e32 v230, v69, v230
	v_add_f32_e32 v230, v70, v230
	v_add_f32_e32 v230, v71, v230
	v_mfma_f32_32x32x16_bf16 v[0:15], v[192:195], v[168:171], v[0:15]
	v_exp_f32_e32 v72, v72
	v_exp_f32_e32 v73, v73
	v_exp_f32_e32 v74, v74
	v_exp_f32_e32 v75, v75
	v_mfma_f32_32x32x16_bf16 v[16:31], v[196:199], v[168:171], v[16:31]
	v_exp_f32_e32 v76, v76
	v_exp_f32_e32 v77, v77
	v_exp_f32_e32 v78, v78
	v_exp_f32_e32 v79, v79
	v_cvt_pk_bf16_f32 v80, v72, v73
	v_cvt_pk_bf16_f32 v81, v74, v75
	v_cvt_pk_bf16_f32 v82, v76, v77
	v_cvt_pk_bf16_f32 v83, v78, v79
	v_add_f32_e32 v230, v72, v230
	v_add_f32_e32 v230, v73, v230
	v_add_f32_e32 v230, v74, v230
	v_add_f32_e32 v230, v75, v230
	v_add_f32_e32 v230, v76, v230
	v_add_f32_e32 v230, v77, v230
	v_add_f32_e32 v230, v78, v230
	v_add_f32_e32 v230, v79, v230
	v_add_f32_e32 v167, v167, v230
	v_mfma_f32_32x32x16_bf16 v[0:15], v[172:175], v[80:83], v[0:15]
	v_mfma_f32_32x32x16_bf16 v[16:31], a[0:3], v[80:83], v[16:31]
.Latt_ot_nors_join:
.Latt_o_end:
	s_andn2_b64 vcc, exec, s[10:11]
	s_cbranch_vccnz .LBB0_456
	s_waitcnt vmcnt(1)
	ds_write_b128 v162, v[120:123] offset:13312
	s_and_saveexec_b64 s[2:3], s[6:7]
	s_cbranch_execz .LBB0_455
	s_waitcnt vmcnt(0)
	ds_write_b128 v164, v[124:127] offset:13440
